# G2 merge loop: 6 loads in flight per thread (2 blocks per iteration), scalar loop control
# speedup vs baseline: 1.1980x; 1.1980x over previous
.LBB0_1336:
	v_lshlrev_b32_e32 v10, 4, v0
	s_mov_b64 s[50:51], s[4:5]
	s_add_u32 s52, s4, 0x2800000
	s_addc_u32 s53, s5, 0
	s_add_u32 s54, s4, 0x5000000
	s_addc_u32 s55, s5, 0
	s_add_u32 s56, s4, 0x7800000
	s_addc_u32 s57, s5, 0
	s_lshl_b64 s[58:59], s[16:17], 1
	s_mov_b32 s46, s80
	s_lshl_b32 s47, s14, 1
	v_add_u32_e32 v11, s16, v10
.Lg2_loop2:
	s_add_i32 s48, s46, s14
	s_cmp_lt_u32 s48, 0x1400
	s_cbranch_scc0 .Lg2_tail
	global_load_dwordx4 v[12:15], v10, s[50:51]
	global_load_dwordx4 v[16:19], v10, s[52:53]
	global_load_dwordx4 v[20:23], v10, s[54:55]
	global_load_dwordx4 v[24:27], v11, s[50:51]
	global_load_dwordx4 v[28:31], v11, s[52:53]
	global_load_dwordx4 v[32:35], v11, s[54:55]
	s_waitcnt vmcnt(3)
	v_lshlrev_b32_e32 v44, 16, v12
	v_and_b32_e32 v45, 0xffff0000, v12
	v_lshlrev_b32_e32 v46, 16, v16
	v_and_b32_e32 v47, 0xffff0000, v16
	v_lshlrev_b32_e32 v48, 16, v20
	v_and_b32_e32 v49, 0xffff0000, v20
	v_pk_add_f32 v[44:45], v[44:45], v[46:47]
	v_pk_add_f32 v[44:45], v[44:45], v[48:49]
	v_cvt_pk_bf16_f32 v36, v44, v45
	v_lshlrev_b32_e32 v44, 16, v13
	v_and_b32_e32 v45, 0xffff0000, v13
	v_lshlrev_b32_e32 v46, 16, v17
	v_and_b32_e32 v47, 0xffff0000, v17
	v_lshlrev_b32_e32 v48, 16, v21
	v_and_b32_e32 v49, 0xffff0000, v21
	v_pk_add_f32 v[44:45], v[44:45], v[46:47]
	v_pk_add_f32 v[44:45], v[44:45], v[48:49]
	v_cvt_pk_bf16_f32 v37, v44, v45
	v_lshlrev_b32_e32 v44, 16, v14
	v_and_b32_e32 v45, 0xffff0000, v14
	v_lshlrev_b32_e32 v46, 16, v18
	v_and_b32_e32 v47, 0xffff0000, v18
	v_lshlrev_b32_e32 v48, 16, v22
	v_and_b32_e32 v49, 0xffff0000, v22
	v_pk_add_f32 v[44:45], v[44:45], v[46:47]
	v_pk_add_f32 v[44:45], v[44:45], v[48:49]
	v_cvt_pk_bf16_f32 v38, v44, v45
	v_lshlrev_b32_e32 v44, 16, v15
	v_and_b32_e32 v45, 0xffff0000, v15
	v_lshlrev_b32_e32 v46, 16, v19
	v_and_b32_e32 v47, 0xffff0000, v19
	v_lshlrev_b32_e32 v48, 16, v23
	v_and_b32_e32 v49, 0xffff0000, v23
	v_pk_add_f32 v[44:45], v[44:45], v[46:47]
	v_pk_add_f32 v[44:45], v[44:45], v[48:49]
	v_cvt_pk_bf16_f32 v39, v44, v45
	global_store_dwordx4 v10, v[36:39], s[56:57]
	s_waitcnt vmcnt(1)
	v_lshlrev_b32_e32 v44, 16, v24
	v_and_b32_e32 v45, 0xffff0000, v24
	v_lshlrev_b32_e32 v46, 16, v28
	v_and_b32_e32 v47, 0xffff0000, v28
	v_lshlrev_b32_e32 v48, 16, v32
	v_and_b32_e32 v49, 0xffff0000, v32
	v_pk_add_f32 v[44:45], v[44:45], v[46:47]
	v_pk_add_f32 v[44:45], v[44:45], v[48:49]
	v_cvt_pk_bf16_f32 v40, v44, v45
	v_lshlrev_b32_e32 v44, 16, v25
	v_and_b32_e32 v45, 0xffff0000, v25
	v_lshlrev_b32_e32 v46, 16, v29
	v_and_b32_e32 v47, 0xffff0000, v29
	v_lshlrev_b32_e32 v48, 16, v33
	v_and_b32_e32 v49, 0xffff0000, v33
	v_pk_add_f32 v[44:45], v[44:45], v[46:47]
	v_pk_add_f32 v[44:45], v[44:45], v[48:49]
	v_cvt_pk_bf16_f32 v41, v44, v45
	v_lshlrev_b32_e32 v44, 16, v26
	v_and_b32_e32 v45, 0xffff0000, v26
	v_lshlrev_b32_e32 v46, 16, v30
	v_and_b32_e32 v47, 0xffff0000, v30
	v_lshlrev_b32_e32 v48, 16, v34
	v_and_b32_e32 v49, 0xffff0000, v34
	v_pk_add_f32 v[44:45], v[44:45], v[46:47]
	v_pk_add_f32 v[44:45], v[44:45], v[48:49]
	v_cvt_pk_bf16_f32 v42, v44, v45
	v_lshlrev_b32_e32 v44, 16, v27
	v_and_b32_e32 v45, 0xffff0000, v27
	v_lshlrev_b32_e32 v46, 16, v31
	v_and_b32_e32 v47, 0xffff0000, v31
	v_lshlrev_b32_e32 v48, 16, v35
	v_and_b32_e32 v49, 0xffff0000, v35
	v_pk_add_f32 v[44:45], v[44:45], v[46:47]
	v_pk_add_f32 v[44:45], v[44:45], v[48:49]
	v_cvt_pk_bf16_f32 v43, v44, v45
	global_store_dwordx4 v11, v[40:43], s[56:57]
	s_add_u32 s50, s50, s58
	s_addc_u32 s51, s51, s59
	s_add_u32 s52, s52, s58
	s_addc_u32 s53, s53, s59
	s_add_u32 s54, s54, s58
	s_addc_u32 s55, s55, s59
	s_add_u32 s56, s56, s58
	s_addc_u32 s57, s57, s59
	s_add_i32 s46, s46, s47
	s_branch .Lg2_loop2
.Lg2_tail:
	s_cmp_lt_u32 s46, 0x1400
	s_cbranch_scc0 .Lg2_done
	global_load_dwordx4 v[12:15], v10, s[50:51]
	global_load_dwordx4 v[16:19], v10, s[52:53]
	global_load_dwordx4 v[20:23], v10, s[54:55]
	s_waitcnt vmcnt(0)
	v_lshlrev_b32_e32 v44, 16, v12
	v_and_b32_e32 v45, 0xffff0000, v12
	v_lshlrev_b32_e32 v46, 16, v16
	v_and_b32_e32 v47, 0xffff0000, v16
	v_lshlrev_b32_e32 v48, 16, v20
	v_and_b32_e32 v49, 0xffff0000, v20
	v_pk_add_f32 v[44:45], v[44:45], v[46:47]
	v_pk_add_f32 v[44:45], v[44:45], v[48:49]
	v_cvt_pk_bf16_f32 v36, v44, v45
	v_lshlrev_b32_e32 v44, 16, v13
	v_and_b32_e32 v45, 0xffff0000, v13
	v_lshlrev_b32_e32 v46, 16, v17
	v_and_b32_e32 v47, 0xffff0000, v17
	v_lshlrev_b32_e32 v48, 16, v21
	v_and_b32_e32 v49, 0xffff0000, v21
	v_pk_add_f32 v[44:45], v[44:45], v[46:47]
	v_pk_add_f32 v[44:45], v[44:45], v[48:49]
	v_cvt_pk_bf16_f32 v37, v44, v45
	v_lshlrev_b32_e32 v44, 16, v14
	v_and_b32_e32 v45, 0xffff0000, v14
	v_lshlrev_b32_e32 v46, 16, v18
	v_and_b32_e32 v47, 0xffff0000, v18
	v_lshlrev_b32_e32 v48, 16, v22
	v_and_b32_e32 v49, 0xffff0000, v22
	v_pk_add_f32 v[44:45], v[44:45], v[46:47]
	v_pk_add_f32 v[44:45], v[44:45], v[48:49]
	v_cvt_pk_bf16_f32 v38, v44, v45
	v_lshlrev_b32_e32 v44, 16, v15
	v_and_b32_e32 v45, 0xffff0000, v15
	v_lshlrev_b32_e32 v46, 16, v19
	v_and_b32_e32 v47, 0xffff0000, v19
	v_lshlrev_b32_e32 v48, 16, v23
	v_and_b32_e32 v49, 0xffff0000, v23
	v_pk_add_f32 v[44:45], v[44:45], v[46:47]
	v_pk_add_f32 v[44:45], v[44:45], v[48:49]
	v_cvt_pk_bf16_f32 v39, v44, v45
	global_store_dwordx4 v10, v[36:39], s[56:57]
.Lg2_done:
.LBB0_1337:
	s_or_b64 exec, exec, s[0:1]
	s_add_i32 s3, s85, 8
	s_cmp_ge_i32 s3, s89
	s_cbranch_scc1 .LBB0_1383
	s_waitcnt vmcnt(0)
	s_waitcnt vmcnt(0) lgkmcnt(0)
	s_barrier
	s_mov_b64 s[0:1], exec
	v_readlane_b32 s4, v252, 3
	v_readlane_b32 s5, v252, 4
	s_and_b64 s[4:5], s[0:1], s[4:5]
	s_mov_b64 exec, s[4:5]
	s_cbranch_execz .LBB0_1382
	v_readlane_b32 s12, v252, 0
	v_readlane_b32 s4, v253, 1
	v_readlane_b32 s13, v252, 1
	s_waitcnt vmcnt(0) expcnt(0) lgkmcnt(0)
	v_mov_b32_e32 v1, s4
	ds_read_b32 v4, v1
	v_readlane_b32 s4, v253, 2
	s_waitcnt lgkmcnt(0)
	v_cmp_ne_u32_e32 vcc, 0, v4
	v_mov_b32_e32 v1, s4
	ds_read_b32 v2, v1
	s_cbranch_vccnz .LBB0_1353
	v_readlane_b32 s6, v252, 7
	v_readlane_b32 s7, v252, 8
	s_load_dwordx2 s[4:5], s[6:7], 0x4
	s_add_u32 s16, s12, 0x1000
	s_addc_u32 s17, s13, 0
	s_add_u32 s18, s12, 0x1100
	s_addc_u32 s19, s13, 0
	s_waitcnt lgkmcnt(0)
	s_mul_i32 s4, s4, s14
	s_add_u32 s14, s12, 0x1200
	s_addc_u32 s15, s13, 0
	s_add_u32 s20, s12, 0x1300
	s_mul_i32 s4, s4, s5
	s_addc_u32 s21, s13, 0
	s_mov_b32 s5, 1
	s_mov_b64 s[22:23], 0
	s_branch .LBB0_1343
